# mLSTM X1 item staging: the 8 K/V row loads + gate load issued together before the item-top barrier (were: one load, vmcnt(0), scatter, next load), counted waits before each LDS scatter
# baseline (speedup 1.0000x reference)
; #define LAS __attribute__((address_space(3)))
; DI void mlstm_x1(const Params& p, LAS unsigned char* lds, int item, int tid_in, int lane_in, int wave) {
;     ...
;     __syncthreads();
; #pragma unroll
;     for (int i = 0; i < 4; ++i) { const int id = tid + 512 * i, rr = id & 127, c = id >> 7;
;         const bf16* src = QKV + (size_t)(base + rr) * NIN0 + head * 128 + c * 8;
;         const u32x4 k = *(const u32x4*)(src + 512), v = *(const u32x4*)(src + 1024);
;         LAS bf16* dk = KTs + (c * 8) * MP + rr; LAS bf16* dv = VTs + (c * 8) * MP + rr;
;         dk[0] = (bf16)(k.x & 0xffffu); dk[MP] = (bf16)(k.x >> 16); dk[2 * MP] = (bf16)(k.y & 0xffffu); dk[3 * MP] = (bf16)(k.y >> 16);
;         dk[4 * MP] = (bf16)(k.z & 0xffffu); dk[5 * MP] = (bf16)(k.z >> 16); dk[6 * MP] = (bf16)(k.w & 0xffffu); dk[7 * MP] = (bf16)(k.w >> 16);
;         dv[0] = (bf16)(v.x & 0xffffu); dv[MP] = (bf16)(v.x >> 16); dv[2 * MP] = (bf16)(v.y & 0xffffu); dv[3 * MP] = (bf16)(v.y >> 16);
;         dv[4 * MP] = (bf16)(v.z & 0xffffu); dv[5 * MP] = (bf16)(v.z >> 16); dv[6 * MP] = (bf16)(v.w & 0xffffu); dv[7 * MP] = (bf16)(v.w >> 16); }
;     { const int u = tid & 127, gi = tid >> 7; sc[gi * 128 + u] = GT[(size_t)(base + u) * 16 + gi * 4 + head]; }
;     __syncthreads();
.LBB0_300:
	v_and_b32_e32 v5, 0x7f, v27
	s_and_b32 s36, s0, 3
	v_add_u32_e32 v0, s6, v5
	s_movk_i32 s0, 0x1600
	v_ashrrev_i32_e32 v6, 4, v27
	v_mad_i64_i32 v[2:3], s[4:5], v0, s0, v[18:19]
	s_lshl_b32 s0, s36, 8
	v_and_b32_e32 v6, -8, v6
	v_lshl_add_u64 v[2:3], v[2:3], 0, s[0:1]
	v_lshlrev_b32_e32 v5, 1, v5
	v_ashrrev_i32_e32 v7, 31, v6
	v_add_u32_e32 v12, s17, v5
	v_add_u32_e32 v5, 0, v5
	s_waitcnt lgkmcnt(0)
	v_lshl_add_u64 v[10:11], v[6:7], 1, v[2:3]
	v_mul_lo_u32 v6, v6, s18
	v_add_u32_e32 v13, v12, v6
	v_add_u32_e32 v14, v5, v6
	global_load_dwordx4 v[48:51], v[10:11], off offset:1024
	global_load_dwordx4 v[52:55], v[10:11], off offset:2048
	v_add_u32_e32 v6, 0x200, v27
	v_ashrrev_i32_e32 v6, 4, v6
	v_and_b32_e32 v6, -8, v6
	v_ashrrev_i32_e32 v7, 31, v6
	v_lshl_add_u64 v[80:81], v[6:7], 1, v[2:3]
	v_mul_lo_u32 v6, v6, s18
	v_add_u32_e32 v86, v12, v6
	v_add_u32_e32 v89, v5, v6
	global_load_dwordx4 v[56:59], v[80:81], off offset:1024
	global_load_dwordx4 v[60:63], v[80:81], off offset:2048
	v_add_u32_e32 v6, 0x400, v27
	v_ashrrev_i32_e32 v6, 4, v6
	v_and_b32_e32 v6, -8, v6
	v_ashrrev_i32_e32 v7, 31, v6
	v_lshl_add_u64 v[82:83], v[6:7], 1, v[2:3]
	v_mul_lo_u32 v6, v6, s18
	v_add_u32_e32 v87, v12, v6
	v_add_u32_e32 v90, v5, v6
	global_load_dwordx4 v[64:67], v[82:83], off offset:1024
	global_load_dwordx4 v[68:71], v[82:83], off offset:2048
	v_add_u32_e32 v6, 0x600, v27
	v_ashrrev_i32_e32 v6, 4, v6
	v_and_b32_e32 v6, -8, v6
	v_ashrrev_i32_e32 v7, 31, v6
	v_lshl_add_u64 v[84:85], v[6:7], 1, v[2:3]
	v_mul_lo_u32 v6, v6, s18
	v_add_u32_e32 v88, v12, v6
	v_add_u32_e32 v91, v5, v6
	global_load_dwordx4 v[72:75], v[84:85], off offset:1024
	global_load_dwordx4 v[76:79], v[84:85], off offset:2048
	v_ashrrev_i32_e32 v1, 31, v0
	v_readlane_b32 s4, v254, 18
	v_lshlrev_b64 v[0:1], 6, v[0:1]
	v_readlane_b32 s5, v254, 19
	s_lshl_b32 s0, s36, 2
	v_and_b32_e32 v4, 63, v27
	v_lshl_add_u64 v[0:1], s[4:5], 0, v[0:1]
	v_readlane_b32 s4, v254, 23
	v_readlane_b32 s5, v254, 24
	s_and_b64 vcc, exec, s[4:5]
	v_ashrrev_i32_e32 v2, 5, v27
	v_and_b32_e32 v2, -4, v2
	v_ashrrev_i32_e32 v3, 31, v2
	v_lshl_add_u64 v[0:1], v[2:3], 2, v[0:1]
	v_lshl_add_u64 v[0:1], v[0:1], 0, s[0:1]
	global_load_dword v0, v[0:1], off
	v_lshl_add_u32 v1, v27, 2, 0
	v_add_u32_e32 v1, 0x19a20, v1
	s_barrier
	s_waitcnt vmcnt(8)
	ds_write_b16 v13, v48
	ds_write_b16_d16_hi v13, v48 offset:272
	ds_write_b16 v13, v49 offset:544
	ds_write_b16_d16_hi v13, v49 offset:816
	ds_write_b16 v13, v50 offset:1088
	ds_write_b16_d16_hi v13, v50 offset:1360
	ds_write_b16 v13, v51 offset:1632
	ds_write_b16_d16_hi v13, v51 offset:1904
	s_waitcnt vmcnt(7)
	ds_write_b16 v14, v52
	ds_write_b16_d16_hi v14, v52 offset:272
	ds_write_b16 v14, v53 offset:544
	ds_write_b16_d16_hi v14, v53 offset:816
	ds_write_b16 v14, v54 offset:1088
	ds_write_b16_d16_hi v14, v54 offset:1360
	ds_write_b16 v14, v55 offset:1632
	ds_write_b16_d16_hi v14, v55 offset:1904
	s_waitcnt vmcnt(6)
	ds_write_b16 v86, v56
	ds_write_b16_d16_hi v86, v56 offset:272
	ds_write_b16 v86, v57 offset:544
	ds_write_b16_d16_hi v86, v57 offset:816
	ds_write_b16 v86, v58 offset:1088
	ds_write_b16_d16_hi v86, v58 offset:1360
	ds_write_b16 v86, v59 offset:1632
	ds_write_b16_d16_hi v86, v59 offset:1904
	s_waitcnt vmcnt(5)
	ds_write_b16 v89, v60
	ds_write_b16_d16_hi v89, v60 offset:272
	ds_write_b16 v89, v61 offset:544
	ds_write_b16_d16_hi v89, v61 offset:816
	ds_write_b16 v89, v62 offset:1088
	ds_write_b16_d16_hi v89, v62 offset:1360
	ds_write_b16 v89, v63 offset:1632
	ds_write_b16_d16_hi v89, v63 offset:1904
	s_waitcnt vmcnt(4)
	ds_write_b16 v87, v64
	ds_write_b16_d16_hi v87, v64 offset:272
	ds_write_b16 v87, v65 offset:544
	ds_write_b16_d16_hi v87, v65 offset:816
	ds_write_b16 v87, v66 offset:1088
	ds_write_b16_d16_hi v87, v66 offset:1360
	ds_write_b16 v87, v67 offset:1632
	ds_write_b16_d16_hi v87, v67 offset:1904
	s_waitcnt vmcnt(3)
	ds_write_b16 v90, v68
	ds_write_b16_d16_hi v90, v68 offset:272
	ds_write_b16 v90, v69 offset:544
	ds_write_b16_d16_hi v90, v69 offset:816
	ds_write_b16 v90, v70 offset:1088
	ds_write_b16_d16_hi v90, v70 offset:1360
	ds_write_b16 v90, v71 offset:1632
	ds_write_b16_d16_hi v90, v71 offset:1904
	s_waitcnt vmcnt(2)
	ds_write_b16 v88, v72
	ds_write_b16_d16_hi v88, v72 offset:272
	ds_write_b16 v88, v73 offset:544
	ds_write_b16_d16_hi v88, v73 offset:816
	ds_write_b16 v88, v74 offset:1088
	ds_write_b16_d16_hi v88, v74 offset:1360
	ds_write_b16 v88, v75 offset:1632
	ds_write_b16_d16_hi v88, v75 offset:1904
	s_waitcnt vmcnt(1)
	ds_write_b16 v91, v76
	ds_write_b16_d16_hi v91, v76 offset:272
	ds_write_b16 v91, v77 offset:544
	ds_write_b16_d16_hi v91, v77 offset:816
	ds_write_b16 v91, v78 offset:1088
	ds_write_b16_d16_hi v91, v78 offset:1360
	ds_write_b16 v91, v79 offset:1632
	ds_write_b16_d16_hi v91, v79 offset:1904
	s_waitcnt vmcnt(0)
	ds_write_b32 v1, v0
	s_waitcnt lgkmcnt(0)
	s_barrier
; #define LAS __attribute__((address_space(3)))
; DI float shfl_up_l(float v, int o, int lane) { return __int_as_float(__builtin_amdgcn_ds_bpermute((lane >= o ? lane - o : lane) << 2, __float_as_int(v))); }
; DI void chunk_scan(int dir, const LAS float* ic, const LAS float* fc, int lane, float& a0, float& a1, float& pm0, float& pm1, float& bc0, float& bc1, float& blast, float& Mall, int& u0, int& u1) {
;     u0 = dir ? 127 - 2 * lane : 2 * lane; u1 = dir ? u0 - 1 : u0 + 1;
;     const float f0 = fc[u0], f1 = fc[u1], i0 = ic[u0], i1 = ic[u1];
;     float S = f0 + f1;
; #pragma unroll
;     for (int o = 1; o < 64; o <<= 1) { const float t = shfl_up_l(S, o, lane); if (lane >= o) S += t; }
;     bc1 = S; bc0 = S - f1; a0 = i0 - bc0; a1 = i1 - bc1;
;     float P = fmaxf(a0, a1);
; #pragma unroll
;     for (int o = 1; o < 64; o <<= 1) { const float t = shfl_up_l(P, o, lane); if (lane >= o) P = fmaxf(P, t); }
;     float Pex = shfl_up_l(P, 1, lane); if (lane == 0) Pex = -INFINITY;
;     pm0 = fmaxf(Pex, a0); pm1 = P;
;     blast = __int_as_float(__builtin_amdgcn_readlane(__float_as_int(bc1), 63)); Mall = __int_as_float(__builtin_amdgcn_readlane(__float_as_int(P), 63));
; }
; DI void mlstm_x1(const Params& p, LAS unsigned char* lds, int item, int tid_in, int lane_in, int wave) {
;     ...
;     if (wave < 2) { const int dir = wave; float a0, a1, pm0, pm1, bc0, bc1, blast, Mall; int u0, u1;
;         chunk_scan(dir, sc + dir * 256, sc + dir * 256 + 128, lane, a0, a1, pm0, pm1, bc0, bc1, blast, Mall, u0, u1);
;         s_w[dir * 128 + u0] = __expf(a0 - Mall) * KSCALE; s_w[dir * 128 + u1] = __expf(a1 - Mall) * KSCALE;
;         if (lane == 0) { float* o = SC + ((size_t)((b * 4 + head) * 2 + dir) * NCH + cp) * 2; o[0] = blast; o[1] = Mall; } }
	s_cbranch_vccnz .LBB0_304
	v_lshlrev_b32_e32 v0, 1, v4
	v_readlane_b32 s4, v254, 20
	v_xor_b32_e32 v1, 0x7f, v0
	v_readlane_b32 s5, v254, 21
	v_cmp_ne_u32_e32 vcc, 0, v4
	v_cmp_gt_u32_e64 s[40:41], 4, v4
	v_cndmask_b32_e64 v0, v1, v0, s[4:5]
	v_lshlrev_b32_e32 v5, 2, v0
	v_add_u32_e32 v2, s14, v5
	ds_read2st64_b32 v[0:1], v2 offset1:2
	v_add_u32_e32 v2, s21, v2
	ds_read2st64_b32 v[2:3], v2 offset1:2
	v_subbrev_co_u32_e64 v6, s[38:39], 0, v4, vcc
	v_lshlrev_b32_e32 v6, 2, v6
	v_cmp_gt_u32_e64 s[38:39], 2, v4
	s_waitcnt lgkmcnt(0)
	v_add_f32_e32 v1, v1, v3
	ds_bpermute_b32 v7, v6, v1
	v_cndmask_b32_e64 v8, -2, 0, s[38:39]
	v_add_lshl_u32 v8, v8, v4, 2
	v_cndmask_b32_e64 v9, -4, 0, s[40:41]
	v_add_lshl_u32 v9, v9, v4, 2
	s_waitcnt lgkmcnt(0)
	v_add_f32_e32 v7, v1, v7
	v_cndmask_b32_e32 v1, v1, v7, vcc
	ds_bpermute_b32 v7, v8, v1
	v_cmp_gt_u32_e64 s[42:43], 8, v4
	v_cmp_gt_u32_e64 s[44:45], 16, v4
	v_lshlrev_b32_e32 v12, 2, v4
	v_cndmask_b32_e64 v10, -8, 0, s[42:43]
	s_waitcnt lgkmcnt(0)
	v_add_f32_e32 v7, v1, v7
	v_cndmask_b32_e64 v1, v7, v1, s[38:39]
	ds_bpermute_b32 v7, v9, v1
	v_add_lshl_u32 v10, v10, v4, 2
	v_cndmask_b32_e64 v11, -16, 0, s[44:45]
	v_add_lshl_u32 v11, v11, v4, 2
	v_and_b32_e32 v12, 0x7c, v12
	s_waitcnt lgkmcnt(0)
	v_add_f32_e32 v7, v1, v7
	v_cndmask_b32_e64 v1, v7, v1, s[40:41]
	ds_bpermute_b32 v7, v10, v1
	v_cmp_gt_u32_e64 s[46:47], 32, v4
	v_add_u32_e32 v5, s33, v5
	s_waitcnt lgkmcnt(0)
	v_add_f32_e32 v7, v1, v7
	v_cndmask_b32_e64 v1, v7, v1, s[42:43]
	ds_bpermute_b32 v7, v11, v1
	s_waitcnt lgkmcnt(0)
	v_add_f32_e32 v7, v1, v7
	v_cndmask_b32_e64 v1, v7, v1, s[44:45]
	ds_bpermute_b32 v7, v12, v1
	s_waitcnt lgkmcnt(0)
	v_add_f32_e32 v7, v1, v7
	v_cndmask_b32_e64 v1, v7, v1, s[46:47]
	v_sub_f32_e32 v3, v1, v3
	v_sub_f32_e32 v2, v2, v1
	v_sub_f32_e32 v0, v0, v3
	v_max_f32_e32 v3, v0, v2
	ds_bpermute_b32 v6, v6, v3
	v_readlane_b32 s6, v1, 63
	s_waitcnt lgkmcnt(0)
	v_max_f32_e32 v6, v6, v6
	v_max_f32_e32 v6, v3, v6
	v_cndmask_b32_e32 v3, v3, v6, vcc
	ds_bpermute_b32 v6, v8, v3
	v_cmp_eq_u32_e32 vcc, 0, v4
	s_waitcnt lgkmcnt(0)
	v_max_f32_e32 v6, v6, v6
	v_max_f32_e32 v6, v3, v6
	v_cndmask_b32_e64 v3, v6, v3, s[38:39]
	ds_bpermute_b32 v6, v9, v3
	s_waitcnt lgkmcnt(0)
	v_max_f32_e32 v6, v6, v6
	v_max_f32_e32 v6, v3, v6
	v_cndmask_b32_e64 v3, v6, v3, s[40:41]
	ds_bpermute_b32 v6, v10, v3
	s_waitcnt lgkmcnt(0)
	v_max_f32_e32 v6, v6, v6
	v_max_f32_e32 v6, v3, v6
	v_cndmask_b32_e64 v3, v6, v3, s[42:43]
	ds_bpermute_b32 v6, v11, v3
	s_waitcnt lgkmcnt(0)
	v_max_f32_e32 v6, v6, v6
	v_max_f32_e32 v6, v3, v6
	v_cndmask_b32_e64 v3, v6, v3, s[44:45]
	ds_bpermute_b32 v6, v12, v3
	v_max_f32_e32 v7, v3, v3
	s_waitcnt lgkmcnt(0)
	v_max_f32_e32 v6, v6, v6
	v_max_f32_e32 v6, v7, v6
	v_cndmask_b32_e64 v3, v6, v3, s[46:47]
	s_nop 0
	v_readlane_b32 s0, v3, 63
	v_add_u32_e32 v3, s21, v5
	s_nop 0
	v_subrev_f32_e32 v0, s0, v0
	v_subrev_f32_e32 v2, s0, v2
	v_mul_f32_e32 v0, 0x3fb8aa3b, v0
	v_mul_f32_e32 v2, 0x3fb8aa3b, v2
	v_exp_f32_e32 v0, v0
	v_exp_f32_e32 v2, v2
	v_mul_f32_e32 v0, 0x3db504f3, v0
	v_mul_f32_e32 v1, 0x3db504f3, v2
	ds_write_b32 v5, v0
	ds_write_b32 v3, v1
	s_and_saveexec_b64 s[4:5], vcc
	s_cbranch_execz .LBB0_303
	s_lshl_b32 s7, s31, 3
	s_lshl_b32 s8, s36, 1
	s_or_b32 s7, s8, s7
	s_or_b32 s7, s7, s87
	s_mul_hi_i32 s9, s7, 34
	s_mul_i32 s7, s7, 34
	s_ashr_i32 s22, s35, 31
	s_add_u32 s8, s7, s35
	s_addc_u32 s9, s9, s22
	s_lshl_b64 s[8:9], s[8:9], 3
	s_add_u32 s8, s3, s8
	s_addc_u32 s9, s80, s9
	v_mov_b32_e32 v0, s6
	v_mov_b32_e32 v1, s0
	global_store_dwordx2 v21, v[0:1], s[8:9]
